# combo + phase C Fourier staging: 8 serialized load/wait/ds_write iterations replaced by all loads in flight with counted waits
# baseline (speedup 1.0000x reference)
.LBB0_579:
	s_lshl_b32 s13, s13, 6
	v_cmp_gt_i32_e32 vcc, s28, v157
	s_and_b32 s13, s13, 0x1c0
	s_waitcnt lgkmcnt(0)
	s_barrier
	s_and_saveexec_b64 s[18:19], vcc
	s_cbranch_execz .LBB0_582
	s_lshl_b32 s88, s13, 1
	v_bfe_u32 v34, v157, 3, 6
	v_mov_b64_e32 v[30:31], s[46:47]
	v_add_u32_e32 v32, s17, v34
	v_mad_i64_i32 v[30:31], s[30:31], v32, s75, v[30:31]
	v_lshl_add_u64 v[30:31], v[30:31], 0, s[88:89]
	v_lshl_add_u64 v[30:31], v[30:31], 0, v[2:3]
	v_add_co_u32_e32 v30, vcc, 0x1a802000, v30
	v_mul_u32_u24_e32 v34, 0x90, v34
	s_mov_b64 s[20:21], 0xb0000
	v_addc_co_u32_e32 v31, vcc, 0, v31, vcc
	v_add_u32_e32 v29, v34, v161
	global_load_dwordx4 v[36:39], v[30:31], off offset:1920
	v_lshl_add_u64 v[30:31], v[30:31], 0, s[20:21]
	global_load_dwordx4 v[40:43], v[30:31], off offset:1920
	v_lshl_add_u64 v[30:31], v[30:31], 0, s[20:21]
	global_load_dwordx4 v[44:47], v[30:31], off offset:1920
	v_lshl_add_u64 v[30:31], v[30:31], 0, s[20:21]
	global_load_dwordx4 v[48:51], v[30:31], off offset:1920
	v_lshl_add_u64 v[30:31], v[30:31], 0, s[20:21]
	s_cmpk_eq_i32 s28, 0x1000
	s_cbranch_scc0 .Lc_stage4
	global_load_dwordx4 v[52:55], v[30:31], off offset:1920
	v_lshl_add_u64 v[30:31], v[30:31], 0, s[20:21]
	global_load_dwordx4 v[56:59], v[30:31], off offset:1920
	v_lshl_add_u64 v[30:31], v[30:31], 0, s[20:21]
	global_load_dwordx4 v[60:63], v[30:31], off offset:1920
	v_lshl_add_u64 v[30:31], v[30:31], 0, s[20:21]
	global_load_dwordx4 v[64:67], v[30:31], off offset:1920
	s_waitcnt vmcnt(7)
	ds_write_b128 v29, v[36:39]
	s_waitcnt vmcnt(6)
	ds_write_b128 v29, v[40:43] offset:9216
	s_waitcnt vmcnt(5)
	ds_write_b128 v29, v[44:47] offset:18432
	s_waitcnt vmcnt(4)
	ds_write_b128 v29, v[48:51] offset:27648
	s_waitcnt vmcnt(3)
	ds_write_b128 v29, v[52:55] offset:36864
	s_waitcnt vmcnt(2)
	ds_write_b128 v29, v[56:59] offset:46080
	s_waitcnt vmcnt(1)
	ds_write_b128 v29, v[60:63] offset:55296
	s_waitcnt vmcnt(0)
	ds_write_b128 v29, v[64:67] offset:64512
	s_branch .LBB0_582
.Lc_stage4:
	s_waitcnt vmcnt(3)
	ds_write_b128 v29, v[36:39]
	s_waitcnt vmcnt(2)
	ds_write_b128 v29, v[40:43] offset:9216
	s_waitcnt vmcnt(1)
	ds_write_b128 v29, v[44:47] offset:18432
	s_waitcnt vmcnt(0)
	ds_write_b128 v29, v[48:51] offset:27648
